# v34: v30 plus running row pointer for the mLSTM chunk output stores (7 address instructions per store reduced to 1)
# speedup vs baseline: 1.0039x; 1.0039x over previous
.LBB0_355:
	s_or_b64 exec, exec, s[38:39]
	s_movk_i32 s100, 0x800
	s_mov_b32 s101, 0
	s_movk_i32 s98, 0x2800
	s_mov_b32 s99, 0
	s_cmp_lg_u64 s[20:21], 0
	s_cbranch_scc1 .Lml_store_fwd
	s_sub_u32 s100, 0, s100
	s_mov_b32 s101, -1
	s_sub_u32 s98, 0, s98
	s_mov_b32 s99, -1
.Lml_store_fwd:
	v_lshrrev_b32_e32 v136, 3, v134
	v_and_b32_e32 v137, 4, v136
	v_lshl_add_u32 v131, v137, 2, 0
	v_and_b32_e32 v130, 31, v134
	v_add_u32_e32 v138, 0x16000, v131
	s_add_i32 s25, s76, 1
	v_lshlrev_b32_e32 v150, 1, v130
	ds_read_b128 v[130:133], v138
	s_and_b64 s[0:1], s[20:21], exec
	s_cselect_b32 s0, s80, s25
	s_lshl_b32 s25, s0, 6
	s_add_i32 s0, s79, 0x180fc
	v_mov_b32_e32 v139, s0
	ds_read_b32 v139, v139
	s_waitcnt lgkmcnt(0)
	v_mul_f32_e32 v66, v66, v130
	v_bitop3_b32 v130, v136, 63, 4 bitop3:0x6c
	v_cndmask_b32_e64 v130, v130, v137, s[20:21]
	v_or_b32_e32 v130, s72, v130
	v_lshl_add_u64 v[134:135], s[22:23], 0, v[150:151]
	v_or_b32_e32 v150, s25, v130
	v_lshlrev_b64 v[140:141], 11, v[150:151]
	v_cvt_pk_bf16_f32 v66, v66, s0
	v_lshl_add_u64 v[140:141], v[134:135], 0, v[140:141]
	v_mul_f32_e32 v67, v67, v131
	global_store_short v[140:141], v66, off
	v_mov_b64_e32 v[250:251], v[140:141]
	v_cvt_pk_bf16_f32 v130, v67, s0
	v_lshl_add_u64 v[250:251], v[250:251], 0, s[100:101]
	global_store_short v[250:251], v130, off
	v_mul_f32_e32 v67, v68, v132
	v_cvt_pk_bf16_f32 v68, v67, s0
	v_lshl_add_u64 v[250:251], v[250:251], 0, s[100:101]
	global_store_short v[250:251], v68, off
	v_mul_f32_e32 v67, v69, v133
	v_cvt_pk_bf16_f32 v68, v67, s0
	v_lshl_add_u64 v[250:251], v[250:251], 0, s[100:101]
	global_store_short v[250:251], v68, off
	ds_read_b128 v[66:69], v138 offset:32
	s_add_i32 s76, s76, -1
	s_addk_i32 s77, 0x100
	s_add_i32 s73, s73, 64
	s_waitcnt lgkmcnt(0)
	v_mul_f32_e32 v66, v70, v66
	v_cvt_pk_bf16_f32 v66, v66, s0
	v_mul_f32_e32 v67, v71, v67
	v_lshl_add_u64 v[250:251], v[250:251], 0, s[98:99]
	global_store_short v[250:251], v66, off
	v_cvt_pk_bf16_f32 v70, v67, s0
	v_lshl_add_u64 v[250:251], v[250:251], 0, s[100:101]
	global_store_short v[250:251], v70, off
	v_mul_f32_e32 v67, v72, v68
	v_cvt_pk_bf16_f32 v68, v67, s0
	v_lshl_add_u64 v[250:251], v[250:251], 0, s[100:101]
	global_store_short v[250:251], v68, off
	v_mul_f32_e32 v67, v73, v69
	v_cvt_pk_bf16_f32 v68, v67, s0
	v_lshl_add_u64 v[250:251], v[250:251], 0, s[100:101]
	global_store_short v[250:251], v68, off
	ds_read_b128 v[66:69], v138 offset:64
	s_waitcnt lgkmcnt(0)
	v_mul_f32_e32 v66, v74, v66
	v_cvt_pk_bf16_f32 v66, v66, s0
	v_mul_f32_e32 v67, v75, v67
	v_lshl_add_u64 v[250:251], v[250:251], 0, s[98:99]
	global_store_short v[250:251], v66, off
	v_cvt_pk_bf16_f32 v70, v67, s0
	v_lshl_add_u64 v[250:251], v[250:251], 0, s[100:101]
	global_store_short v[250:251], v70, off
	v_mul_f32_e32 v67, v76, v68
	v_cvt_pk_bf16_f32 v68, v67, s0
	v_lshl_add_u64 v[250:251], v[250:251], 0, s[100:101]
	global_store_short v[250:251], v68, off
	v_mul_f32_e32 v67, v77, v69
	v_cvt_pk_bf16_f32 v68, v67, s0
	v_lshl_add_u64 v[250:251], v[250:251], 0, s[100:101]
	global_store_short v[250:251], v68, off
	ds_read_b128 v[66:69], v138 offset:96
	s_waitcnt lgkmcnt(0)
	v_mul_f32_e32 v66, v78, v66
	v_cvt_pk_bf16_f32 v66, v66, s0
	v_mul_f32_e32 v67, v79, v67
	v_lshl_add_u64 v[250:251], v[250:251], 0, s[98:99]
	global_store_short v[250:251], v66, off
	v_cvt_pk_bf16_f32 v70, v67, s0
	v_lshl_add_u64 v[250:251], v[250:251], 0, s[100:101]
	global_store_short v[250:251], v70, off
	v_mul_f32_e32 v67, v80, v68
	v_cvt_pk_bf16_f32 v68, v67, s0
	v_lshl_add_u64 v[250:251], v[250:251], 0, s[100:101]
	global_store_short v[250:251], v68, off
	v_mul_f32_e32 v67, v81, v69
	v_cvt_pk_bf16_f32 v68, v67, s0
	v_lshl_add_u64 v[250:251], v[250:251], 0, s[100:101]
	global_store_short v[250:251], v68, off
	ds_read_b128 v[66:69], v138 offset:128
	s_waitcnt lgkmcnt(0)
	v_mul_f32_e32 v66, v82, v66
	v_cvt_pk_bf16_f32 v66, v66, s0
	v_mul_f32_e32 v67, v83, v67
	v_lshl_add_u64 v[250:251], v[250:251], 0, s[98:99]
	global_store_short v[250:251], v66, off
	v_cvt_pk_bf16_f32 v70, v67, s0
	v_lshl_add_u64 v[250:251], v[250:251], 0, s[100:101]
	global_store_short v[250:251], v70, off
	v_mul_f32_e32 v67, v84, v68
	v_cvt_pk_bf16_f32 v68, v67, s0
	v_lshl_add_u64 v[250:251], v[250:251], 0, s[100:101]
	global_store_short v[250:251], v68, off
	v_mul_f32_e32 v67, v85, v69
	v_cvt_pk_bf16_f32 v68, v67, s0
	v_lshl_add_u64 v[250:251], v[250:251], 0, s[100:101]
	global_store_short v[250:251], v68, off
	ds_read_b128 v[66:69], v138 offset:160
	s_waitcnt lgkmcnt(0)
	v_mul_f32_e32 v66, v86, v66
	v_cvt_pk_bf16_f32 v66, v66, s0
	v_mul_f32_e32 v67, v87, v67
	v_lshl_add_u64 v[250:251], v[250:251], 0, s[98:99]
	global_store_short v[250:251], v66, off
	v_cvt_pk_bf16_f32 v70, v67, s0
	v_lshl_add_u64 v[250:251], v[250:251], 0, s[100:101]
	global_store_short v[250:251], v70, off
	v_mul_f32_e32 v67, v88, v68
	v_cvt_pk_bf16_f32 v68, v67, s0
	v_lshl_add_u64 v[250:251], v[250:251], 0, s[100:101]
	global_store_short v[250:251], v68, off
	v_mul_f32_e32 v67, v89, v69
	v_cvt_pk_bf16_f32 v68, v67, s0
	v_lshl_add_u64 v[250:251], v[250:251], 0, s[100:101]
	global_store_short v[250:251], v68, off
	ds_read_b128 v[66:69], v138 offset:192
	s_waitcnt lgkmcnt(0)
	v_mul_f32_e32 v66, v90, v66
	v_cvt_pk_bf16_f32 v66, v66, s0
	v_mul_f32_e32 v67, v91, v67
	v_lshl_add_u64 v[250:251], v[250:251], 0, s[98:99]
	global_store_short v[250:251], v66, off
	v_cvt_pk_bf16_f32 v70, v67, s0
	v_lshl_add_u64 v[250:251], v[250:251], 0, s[100:101]
	global_store_short v[250:251], v70, off
	v_mul_f32_e32 v67, v92, v68
	v_cvt_pk_bf16_f32 v68, v67, s0
	v_lshl_add_u64 v[250:251], v[250:251], 0, s[100:101]
	global_store_short v[250:251], v68, off
	v_mul_f32_e32 v67, v93, v69
	v_cvt_pk_bf16_f32 v68, v67, s0
	v_lshl_add_u64 v[250:251], v[250:251], 0, s[100:101]
	global_store_short v[250:251], v68, off
	ds_read_b128 v[66:69], v138 offset:224
	s_waitcnt lgkmcnt(0)
	v_mul_f32_e32 v66, v94, v66
	v_cvt_pk_bf16_f32 v66, v66, s0
	v_mul_f32_e32 v67, v95, v67
	v_lshl_add_u64 v[250:251], v[250:251], 0, s[98:99]
	global_store_short v[250:251], v66, off
	v_cvt_pk_bf16_f32 v70, v67, s0
	v_lshl_add_u64 v[250:251], v[250:251], 0, s[100:101]
	global_store_short v[250:251], v70, off
	v_mul_f32_e32 v67, v96, v68
	v_cvt_pk_bf16_f32 v68, v67, s0
	v_lshl_add_u64 v[250:251], v[250:251], 0, s[100:101]
	global_store_short v[250:251], v68, off
	v_mul_f32_e32 v67, v97, v69
	v_cvt_pk_bf16_f32 v68, v67, s0
	v_add_f32_e32 v155, v153, v139
	s_cmpk_eq_i32 s77, 0x2000
	s_mov_b32 s80, s78
	v_lshl_add_u64 v[250:251], v[250:251], 0, s[100:101]
	global_store_short v[250:251], v68, off
	s_cbranch_scc1 .LBB0_346
